# v3 + phase 8 and phase 10 tile order reversed (phase 9 forward): alternate directions so each GEMM phase first reads what the previous phase wrote last
# speedup vs baseline: 1.0191x; 1.0011x over previous
; template <class Epi, class Sched, bool SP2 = PG8_SP2>
; __device__ __forceinline__ void gemm_phase(LAS unsigned char* lds, const Gemm g, const Sched& S, const Epi& E) {
;     const int tid = threadIdx.x, wid = __builtin_amdgcn_readfirstlane(tid >> 6), lane = tid & 63, wr = wid >> 2, wc = wid & 3, fr = lane & 15, fq = lane >> 4;
;     const int K = g.K, nt = K / BK, lda = g.lda;
;     unsigned voffA[2], voffB[2];
; #pragma unroll
;     for (int i = 0; i < 2; ++i) { int R, C; stage_rc(tid * 16 + i * 8192, R, C); const int Rb = Epi::PERM ? ((R & ~31) + perm32(R & 31)) : R;
;         voffA[i] = (unsigned)(R * lda + C) * 2u; voffB[i] = (unsigned)(Rb * K + C) * 2u; }
;     const size_t kstep = (size_t)(BK * 2);
;     const size_t hstepA = (size_t)HALF * lda * 2, hstepB = (size_t)HALF * K * 2;
;     const size_t tstepA = 2 * hstepA, tstepB = 2 * hstepB;
;     const unsigned ldsw = (unsigned)wid * 1024u;
;     const int aoff = lds_byte(wr * 64 + fr, fq * 8), boff = lds_byte(wc * 32 + fr, fq * 8);
;     ...
;     Unit cur, nxt; int ui = 0;
;     if (!S.next(0, cur)) return;
;     f32x4 acc[2][2][4][2];
; #pragma unroll
;     for (int a = 0; a < 2; ++a)
; #pragma unroll
;         for (int b = 0; b < 2; ++b)
; #pragma unroll
;             for (int m = 0; m < 4; ++m)
; #pragma unroll
;                 for (int n = 0; n < 2; ++n) acc[a][b][m][n] = (f32x4){0.f, 0.f, 0.f, 0.f};
;     bf16x8 At[4][2], B0[2][2], B1[2][2];
;     const char* cA = (const char*)g.A + (size_t)cur.pm * tstepA; const char* cB = (const char*)g.Bt + (size_t)cur.pn * tstepB;
;     if constexpr (SP2) {
;     PG8_STAGE(PG8_SB(0, 0), cB, voffB); PG8_STAGE(PG8_SB(0, 1), cB + hstepB, voffB); PG8_STAGE(PG8_SA(0, 0), cA, voffA); PG8_STAGE(PG8_SA(0, 1), cA + hstepA, voffA);
;     if (wr == 1) PG8_BAR;
;     PG8_WAIT_V(2); PG8_BAR;
;     PG8_STAGE(PG8_SB(1, 0), cB + kstep, voffB); PG8_STAGE(PG8_SA(1, 0), cA + kstep, voffA); PG8_STAGE(PG8_SB(1, 1), cB + hstepB + kstep, voffB);
;     PG8_WAIT_V(6); PG8_BAR;
;     } else {
;     PG8_STAGE(PG8_SB(0, 0), cB, voffB); PG8_STAGE(PG8_SA(0, 0), cA, voffA); PG8_STAGE(PG8_SB(0, 1), cB + hstepB, voffB); PG8_STAGE(PG8_SA(0, 1), cA + hstepA, voffA);
;     if (wr == 1) PG8_BAR;
;     PG8_WAIT_V(4); PG8_BAR;
;     PG8_STAGE(PG8_SB(1, 0), cB + kstep, voffB); PG8_STAGE(PG8_SA(1, 0), cA + kstep, voffA); PG8_STAGE(PG8_SB(1, 1), cB + hstepB + kstep, voffB);
;     PG8_WAIT_V(6); PG8_BAR;
.LBB0_922:
	s_cmp_lt_i32 s2, 9
	s_cselect_b64 s[0:1], -1, 0
	s_cmp_gt_i32 s3, 8
	s_cselect_b64 s[2:3], -1, 0
	s_and_b64 s[6:7], s[0:1], s[2:3]
	s_andn2_b64 vcc, exec, s[6:7]
	s_cbranch_vccnz .LBB0_939
	s_cmpk_gt_i32 s88, 0xaff
	v_readfirstlane_b32 s2, v222
	s_cbranch_scc1 .LBB0_939
	s_load_dwordx2 s[4:5], s[78:79], 0xc0
	v_lshrrev_b32_e32 v0, 5, v222
	v_lshrrev_b32_e32 v2, 1, v222
	v_and_b32_e32 v0, 4, v0
	s_waitcnt lgkmcnt(0)
	v_bfe_u32 v1, v222, 2, 2
	v_and_b32_e32 v11, 24, v2
	v_or3_b32 v0, v0, v1, v11
	v_lshlrev_b32_e32 v1, 4, v222
	v_add_u32_e32 v8, 0x2000, v1
	v_lshrrev_b32_e32 v2, 7, v8
	s_movk_i32 s0, 0xe0
	v_and_b32_e32 v4, 32, v222
	s_add_u32 s33, s4, 0x8000000
	v_and_or_b32 v3, v2, s0, v0
	v_bitop3_b32 v9, v1, v4, 48 bitop3:0x6c
	v_and_b32_e32 v10, 64, v222
	v_bfe_u32 v12, v222, 2, 4
	s_movk_i32 s0, 0xf0
	s_addc_u32 s34, s5, 0
	v_or_b32_e32 v1, v9, v10
	v_and_or_b32 v2, v2, s0, v12
	s_add_u32 s35, s4, 0x1a00000
	s_waitcnt vmcnt(0)
	v_lshl_or_b32 v130, v2, 12, v1
	v_lshrrev_b32_e32 v2, 3, v222
	s_movk_i32 s0, 0x60
	s_addc_u32 s36, s5, 0
	v_and_or_b32 v0, v2, s0, v0
	s_movk_i32 s0, 0x70
	s_ashr_i32 s38, s88, 31
	v_lshl_or_b32 v132, v0, 12, v1
	v_and_or_b32 v0, v2, s0, v12
	s_lshr_b32 s0, s38, 29
	s_add_i32 s0, s88, s0
	s_lshr_b32 s14, s2, 6
	s_ashr_i32 s1, s0, 3
	s_and_b32 s0, s0, -8
	s_lshr_b32 s3, s2, 8
	s_lshl_b32 s37, s14, 10
	s_sub_i32 s0, s88, s0
	s_cmp_lt_i32 s0, 0
	s_movk_i32 s39, 0x161
	s_cselect_b32 s8, s39, 0x160
	s_mul_i32 s0, s8, s0
	s_add_i32 s0, s0, s1
	s_addk_i32 s0, 0x140
	s_mul_hi_i32 s1, s0, 0x2e8ba2e9
	s_lshr_b32 s8, s1, 31
	s_ashr_i32 s1, s1, 5
	s_add_i32 s1, s1, s8
	s_lshl_b32 s8, s1, 3
	s_mulk_i32 s1, 0xb0
	s_sub_i32 s0, s0, s1
	s_sext_i32_i16 s1, s0
	s_bfe_u32 s1, s1, 0x3001c
	s_add_i32 s1, s0, s1
	s_sext_i32_i16 s9, s1
	s_and_b32 s1, s1, 0xfff8
	s_sub_i32 s0, s0, s1
	s_sext_i32_i16 s0, s0
	s_lshr_b32 s16, s9, 3
	s_add_i32 s26, s8, s0
	s_ashr_i32 s27, s26, 31
	s_bfe_i64 s[8:9], s[16:17], 0x100000
	s_lshl_b64 s[0:1], s[26:27], 20
	s_lshl_b64 s[8:9], s[8:9], 20
	s_add_u32 s28, s35, s8
	s_addc_u32 s29, s36, s9
	s_add_i32 s27, s37, 0
	s_add_i32 m0, s27, 0x10000
	v_lshl_or_b32 v128, v3, 12, v1
	global_load_lds_dwordx4 v132, s[28:29]
	s_add_i32 m0, s27, 0x12000
	s_add_u32 s8, s28, 0x80000
	global_load_lds_dwordx4 v128, s[28:29]
	s_addc_u32 s9, s29, 0
	s_add_i32 m0, s27, 0x14000
	v_lshl_or_b32 v134, v0, 12, v1
	global_load_lds_dwordx4 v132, s[8:9]
	s_add_i32 m0, s27, 0x16000
	s_add_u32 s0, s33, s0
	s_addc_u32 s1, s34, s1
	s_add_i32 s40, s27, 0x2000
	global_load_lds_dwordx4 v128, s[8:9]
	s_mov_b32 m0, s27
	s_add_u32 s8, s0, 0x80000
	global_load_lds_dwordx4 v134, s[0:1]
	s_mov_b32 m0, s40
	s_addc_u32 s9, s1, 0
	s_add_i32 s41, s27, 0x4000
	global_load_lds_dwordx4 v130, s[0:1]
	s_mov_b32 m0, s41
	s_add_i32 s42, s27, 0x6000
	global_load_lds_dwordx4 v134, s[8:9]
	s_mov_b32 m0, s42
	v_mov_b32_e32 v133, 0
	global_load_lds_dwordx4 v130, s[8:9]
	v_mov_b32_e32 v129, v133
	v_mov_b32_e32 v135, v133
	v_mov_b32_e32 v131, v133
	s_cmp_eq_u32 s3, 1
	s_mov_b32 s43, 0
	v_lshl_add_u64 v[6:7], s[28:29], 0, v[132:133]
	v_lshl_add_u64 v[4:5], s[28:29], 0, v[128:129]
	v_lshl_add_u64 v[0:1], s[0:1], 0, v[134:135]
	s_cselect_b64 s[8:9], -1, 0
	s_cmp_lg_u32 s3, 1
	v_lshl_add_u64 v[2:3], s[0:1], 0, v[130:131]
	s_cbranch_scc1 .LBB0_926
	s_barrier

;     __device__ bool next(int i, Unit& u) const {
;         const long L = (long)i * G + c; if (L >= nwg) return false;
;         int wgid = (int)L; { const int q = nwg / NXCD, r = nwg % NXCD, xcd = wgid % NXCD, off = wgid / NXCD; wgid = (xcd < r ? xcd * (q + 1) : r * (q + 1) + (xcd - r) * q) + off; }
;         const int nig = WGM * nN, gid = wgid / nig, fm = gid * WGM, gsz = (nM - fm) < WGM ? (nM - fm) : WGM;
;         u.pm = fm + ((wgid % nig) % gsz); u.pn = (wgid % nig) / gsz; return true;
;     }
; template <class Epi, class Sched, bool SP2 = PG8_SP2>
; __device__ __forceinline__ void gemm_phase(LAS unsigned char* lds, const Gemm g, const Sched& S, const Epi& E) {
;     ...
;         const bool has_next = S.next(ui + 1, nxt);
;         const char* nA = has_next ? (const char*)g.A + (size_t)nxt.pm * tstepA : cA; const char* nB = has_next ? (const char*)g.Bt + (size_t)nxt.pn * tstepB : cB;
.LBB0_929:
	s_add_i32 s43, s43, 1
	s_sub_i32 s2, 10, s43
	s_mul_i32 s3, s2, s86
	s_add_i32 s22, s3, s88
	s_cmp_lt_i32 s2, 0
	s_cselect_b32 s22, 0xb00, s22
	s_mov_b32 s23, 0
	v_cmp_gt_i64_e32 vcc, s[22:23], v[142:143]
	v_cmp_lt_i64_e64 s[4:5], s[22:23], v[140:141]
	s_cbranch_vccnz .LBB0_931
	s_ashr_i32 s2, s22, 31
	s_lshr_b32 s2, s2, 29
	s_add_i32 s2, s22, s2
	s_ashr_i32 s3, s2, 3
	s_and_b32 s2, s2, -8
	s_sub_i32 s2, s22, s2
	s_cmp_lt_i32 s2, 0
	s_cselect_b32 s18, s39, 0x160
	s_mul_i32 s2, s18, s2
	s_add_i32 s2, s2, s3
	s_mul_hi_i32 s3, s2, 0x2e8ba2e9
	s_lshr_b32 s18, s3, 31
	s_ashr_i32 s3, s3, 5
	s_add_i32 s3, s3, s18
	s_lshl_b32 s19, s3, 3
	s_sub_i32 s18, 0x80, s19
	s_min_i32 s20, s18, 8
	s_abs_i32 s18, s20
	v_cvt_f32_u32_e32 v0, s18
	s_sub_i32 s22, 0, s18
	s_mulk_i32 s3, 0xb0
	s_sub_i32 s2, s2, s3
	v_rcp_iflag_f32_e32 v0, v0
	s_abs_i32 s3, s2
	s_xor_b32 s21, s2, s20
	s_ashr_i32 s21, s21, 31
	v_mul_f32_e32 v0, 0x4f7ffffe, v0
	v_cvt_u32_f32_e32 v0, v0
	s_nop 0
	v_readfirstlane_b32 s23, v0
	s_mul_i32 s22, s22, s23
	s_mul_hi_u32 s22, s23, s22
	s_add_i32 s23, s23, s22
	s_mul_hi_u32 s22, s3, s23
	s_mul_i32 s23, s22, s18
	s_sub_i32 s3, s3, s23
	s_add_i32 s24, s22, 1
	s_sub_i32 s23, s3, s18
	s_cmp_ge_u32 s3, s18
	s_cselect_b32 s22, s24, s22
	s_cselect_b32 s3, s23, s3
	s_add_i32 s23, s22, 1
	s_cmp_ge_u32 s3, s18
	s_cselect_b32 s3, s23, s22
	s_xor_b32 s3, s3, s21
	s_sub_i32 s18, s3, s21
	s_mul_i32 s3, s18, s20
	s_sub_i32 s2, s2, s3
	s_add_i32 s20, s2, s19

; template <class Epi, class Sched, bool SP2 = PG8_SP2>
; __device__ __forceinline__ void gemm_phase(LAS unsigned char* lds, const Gemm g, const Sched& S, const Epi& E) {
;     const int tid = threadIdx.x, wid = __builtin_amdgcn_readfirstlane(tid >> 6), lane = tid & 63, wr = wid >> 2, wc = wid & 3, fr = lane & 15, fq = lane >> 4;
;     const int K = g.K, nt = K / BK, lda = g.lda;
;     unsigned voffA[2], voffB[2];
; #pragma unroll
;     for (int i = 0; i < 2; ++i) { int R, C; stage_rc(tid * 16 + i * 8192, R, C); const int Rb = Epi::PERM ? ((R & ~31) + perm32(R & 31)) : R;
;         voffA[i] = (unsigned)(R * lda + C) * 2u; voffB[i] = (unsigned)(Rb * K + C) * 2u; }
;     const size_t kstep = (size_t)(BK * 2);
;     const size_t hstepA = (size_t)HALF * lda * 2, hstepB = (size_t)HALF * K * 2;
;     const size_t tstepA = 2 * hstepA, tstepB = 2 * hstepB;
;     const unsigned ldsw = (unsigned)wid * 1024u;
;     const int aoff = lds_byte(wr * 64 + fr, fq * 8), boff = lds_byte(wc * 32 + fr, fq * 8);
;     ...
;     Unit cur, nxt; int ui = 0;
;     if (!S.next(0, cur)) return;
;     f32x4 acc[2][2][4][2];
; #pragma unroll
;     for (int a = 0; a < 2; ++a)
; #pragma unroll
;         for (int b = 0; b < 2; ++b)
; #pragma unroll
;             for (int m = 0; m < 4; ++m)
; #pragma unroll
;                 for (int n = 0; n < 2; ++n) acc[a][b][m][n] = (f32x4){0.f, 0.f, 0.f, 0.f};
;     bf16x8 At[4][2], B0[2][2], B1[2][2];
;     const char* cA = (const char*)g.A + (size_t)cur.pm * tstepA; const char* cB = (const char*)g.Bt + (size_t)cur.pn * tstepB;
;     if constexpr (SP2) {
;     PG8_STAGE(PG8_SB(0, 0), cB, voffB); PG8_STAGE(PG8_SB(0, 1), cB + hstepB, voffB); PG8_STAGE(PG8_SA(0, 0), cA, voffA); PG8_STAGE(PG8_SA(0, 1), cA + hstepA, voffA);
;     if (wr == 1) PG8_BAR;
;     PG8_WAIT_V(2); PG8_BAR;
;     PG8_STAGE(PG8_SB(1, 0), cB + kstep, voffB); PG8_STAGE(PG8_SA(1, 0), cA + kstep, voffA); PG8_STAGE(PG8_SB(1, 1), cB + hstepB + kstep, voffB);
;     PG8_WAIT_V(6); PG8_BAR;
;     } else {
;     PG8_STAGE(PG8_SB(0, 0), cB, voffB); PG8_STAGE(PG8_SA(0, 0), cA, voffA); PG8_STAGE(PG8_SB(0, 1), cB + hstepB, voffB); PG8_STAGE(PG8_SA(0, 1), cA + hstepA, voffA);
;     if (wr == 1) PG8_BAR;
;     PG8_WAIT_V(4); PG8_BAR;
;     PG8_STAGE(PG8_SB(1, 0), cB + kstep, voffB); PG8_STAGE(PG8_SA(1, 0), cA + kstep, voffA); PG8_STAGE(PG8_SB(1, 1), cB + hstepB + kstep, voffB);
;     PG8_WAIT_V(6); PG8_BAR;
.LBB0_1074:
	s_waitcnt lgkmcnt(0)
	s_add_u32 s31, s10, 0x26000000
	s_addc_u32 s33, s11, 0
	s_add_u32 s34, s10, 0x4600000
	s_addc_u32 s35, s11, 0
	s_add_i32 s1, s4, s1
	s_addk_i32 s1, 0x60
	s_ashr_i32 s4, s1, 31
	s_lshr_b32 s4, s4, 26
	s_add_i32 s4, s1, s4
	s_ashr_i32 s5, s4, 6
	s_and_b32 s4, s4, 0xffc0
	s_sub_i32 s4, s1, s4
	s_bfe_i32 s1, s4, 0x80000
	s_bfe_u32 s1, s1, 0x3000c
	s_add_i32 s6, s4, s1
	v_lshlrev_b32_e32 v0, 4, v222
	v_and_b32_e32 v1, 32, v222
	s_bfe_i32 s1, s6, 0x80000
	s_and_b32 s6, s6, 0xf8
	v_bfe_u32 v2, v222, 2, 4
	v_bitop3_b32 v8, v0, v1, 48 bitop3:0x6c
	v_lshrrev_b32_e32 v3, 3, v222
	s_movk_i32 s3, 0x70
	v_add_u32_e32 v0, 0x2000, v0
	s_sub_i32 s4, s4, s6
	v_and_or_b32 v3, v3, s3, v2
	v_lshrrev_b32_e32 v0, 7, v0
	s_movk_i32 s3, 0xf0
	s_lshl_b32 s5, s5, 3
	s_sext_i32_i16 s7, s1
	s_sext_i32_i8 s4, s4
	v_and_or_b32 v0, v0, s3, v2
	s_lshr_b32 s3, s2, 6
	s_add_i32 s53, s5, s4
	s_ashr_i32 s4, s7, 3
	s_lshr_b32 s0, s2, 8
	s_lshl_b32 s36, s3, 10
	s_lshr_b32 s1, s7, 3
	s_mul_hi_i32 s5, s4, 0x2c0000
	s_mul_i32 s4, s4, 0x2c0000
	v_and_b32_e32 v9, 64, v222
	s_add_u32 s26, s34, s4
	v_or_b32_e32 v1, v8, v9
	v_mul_u32_u24_e32 v10, 0x2c00, v3
	s_addc_u32 s27, s35, s5
	s_add_i32 s37, s36, 0
	s_waitcnt vmcnt(0)
	v_or_b32_e32 v128, v10, v1
	s_add_i32 m0, s37, 0x10000
	v_mul_u32_u24_e32 v11, 0x2c00, v0
	global_load_lds_dwordx4 v128, s[26:27]
	s_add_i32 m0, s37, 0x12000
	v_or_b32_e32 v130, v11, v1
	s_add_u32 s4, s26, 0x160000
	global_load_lds_dwordx4 v130, s[26:27]
	s_addc_u32 s5, s27, 0
	s_add_i32 m0, s37, 0x14000
	s_mul_i32 s10, s53, 0x2c0000
	global_load_lds_dwordx4 v128, s[4:5]
	s_add_i32 m0, s37, 0x16000
	s_mul_hi_i32 s6, s53, 0x2c0000
	s_add_u32 s24, s31, s10
	s_addc_u32 s25, s33, s6
	s_add_i32 s38, s37, 0x2000
	global_load_lds_dwordx4 v130, s[4:5]
	s_mov_b32 m0, s37
	s_add_u32 s4, s24, 0x160000
	global_load_lds_dwordx4 v128, s[24:25]
	s_mov_b32 m0, s38
	s_addc_u32 s5, s25, 0
	s_add_i32 s39, s37, 0x4000
	global_load_lds_dwordx4 v130, s[24:25]
	s_mov_b32 m0, s39
	s_add_i32 s40, s37, 0x6000
	global_load_lds_dwordx4 v128, s[4:5]
	s_mov_b32 m0, s40
	v_mov_b32_e32 v129, 0
	global_load_lds_dwordx4 v130, s[4:5]
	v_mov_b32_e32 v131, v129
	s_cmp_eq_u32 s0, 1
	s_mov_b32 s41, 0
	v_lshl_add_u64 v[6:7], s[26:27], 0, v[128:129]
	v_lshl_add_u64 v[4:5], s[26:27], 0, v[130:131]
	s_mov_b64 s[6:7], 0x160000
	v_lshl_add_u64 v[0:1], s[24:25], 0, v[128:129]
	s_cselect_b64 s[10:11], -1, 0
	s_cmp_lg_u32 s0, 1
	v_lshl_add_u64 v[2:3], s[24:25], 0, v[130:131]
	s_cbranch_scc1 .LBB0_1076
	s_barrier

;     __device__ bool next(int i, Unit& u) const {
;         const long L = (long)i * G + c; if (L >= nwg) return false;
;         int wgid = (int)L; { const int q = nwg / NXCD, r = nwg % NXCD, xcd = wgid % NXCD, off = wgid / NXCD; wgid = (xcd < r ? xcd * (q + 1) : r * (q + 1) + (xcd - r) * q) + off; }
;         const int nig = WGM * nN, gid = wgid / nig, fm = gid * WGM, gsz = (nM - fm) < WGM ? (nM - fm) : WGM;
;         u.pm = fm + ((wgid % nig) % gsz); u.pn = (wgid % nig) / gsz; return true;
;     }
; template <class Epi, class Sched, bool SP2 = PG8_SP2>
; __device__ __forceinline__ void gemm_phase(LAS unsigned char* lds, const Gemm g, const Sched& S, const Epi& E) {
;     ...
;         const bool has_next = S.next(ui + 1, nxt);
;         const char* nA = has_next ? (const char*)g.A + (size_t)nxt.pm * tstepA : cA; const char* nB = has_next ? (const char*)g.Bt + (size_t)nxt.pn * tstepB : cB;
.LBB0_1079:
	s_add_i32 s41, s41, 1
	s_sub_i32 s0, 3, s41
	s_mul_i32 s1, s0, s86
	s_add_i32 s1, s1, s88
	s_cmp_lt_i32 s0, 0
	s_cselect_b32 s0, 0x400, s1
	s_mov_b32 s1, 0
	v_cmp_gt_i64_e32 vcc, s[0:1], v[138:139]
	v_cmp_lt_i64_e64 s[4:5], s[0:1], v[136:137]
	s_cbranch_vccnz .LBB0_1085
	s_ashr_i32 s1, s0, 31
	s_lshr_b32 s1, s1, 29
	s_add_i32 s2, s0, s1
	s_and_b32 s1, s2, -8
	s_sub_i32 s3, s0, s1
	s_cmp_gt_i32 s3, -1
	s_mov_b64 s[0:1], -1
	s_cbranch_scc0 .LBB0_1082
	s_lshl_b32 s22, s3, 7
	s_mov_b64 s[0:1], 0
